# attention: s_setprio 1/0 around the QK and PV MFMA clusters (T5 form; the loop had no priority control)
# baseline (speedup 1.0000x reference)
; __device__ __forceinline__ void att_qk_sm(const LAS unsigned char* kb, int klane, const bf16x8 (&qf)[12], f32x16 (&o)[4], float& mrun, float& lrun, bf16x8 (&pb)[4]) {
;     constexpr int KP = 400;
;     f32x16 s0, s1;
; #pragma unroll
;     for (int i = 0; i < 16; ++i) { s0[i] = 0.f; s1[i] = 0.f; }
;     bf16x8 ka[3][2];
; #pragma unroll
;     for (int g = 0; g < 2; ++g) { ka[g][0] = *(const LAS bf16x8*)(kb + klane + g * 32); ka[g][1] = *(const LAS bf16x8*)(kb + klane + 32 * KP + g * 32); }
; #pragma unroll
;     for (int g = 0; g < 12; ++g) {
;         if (g < 10) { ka[(g + 2) % 3][0] = *(const LAS bf16x8*)(kb + klane + (g + 2) * 32); ka[(g + 2) % 3][1] = *(const LAS bf16x8*)(kb + klane + 32 * KP + (g + 2) * 32); }
;         __builtin_amdgcn_sched_barrier(0);
;         s0 = __builtin_amdgcn_mfma_f32_32x32x16_bf16(ka[g % 3][0], qf[g], s0, 0, 0, 0);
;         s1 = __builtin_amdgcn_mfma_f32_32x32x16_bf16(ka[g % 3][1], qf[g], s1, 0, 0, 0);
;         __builtin_amdgcn_sched_barrier(0);
;     }
; __device__ __forceinline__ void att_pv(const LAS unsigned char* kb, int vlane, const bf16x8 (&pb)[4], f32x16 (&o)[4]) {
;     constexpr int VP = 320;
;     s16x4 vlo[2][4], vhi[2][4];
;     const unsigned vaddr = (unsigned)(unsigned long)(kb + vlane);
; #pragma unroll
;     for (int d = 0; d < 4; ++d) { TR_READ(vlo[0][d], vaddr, d * 64); TR_READ(vhi[0][d], vaddr, 8 * VP + d * 64); }
; #pragma unroll
;     for (int ks = 0; ks < 4; ++ks) {
;         if (ks < 3) {
; #pragma unroll
;             for (int d = 0; d < 4; ++d) { TR_READ(vlo[(ks + 1) & 1][d], vaddr, ((ks + 1) * 16) * VP + d * 64); TR_READ(vhi[(ks + 1) & 1][d], vaddr, ((ks + 1) * 16 + 8) * VP + d * 64); }
;             TR_WAIT4(8, vlo[ks & 1][0], vlo[ks & 1][1], vlo[ks & 1][2], vlo[ks & 1][3]); TR_WAIT4(8, vhi[ks & 1][0], vhi[ks & 1][1], vhi[ks & 1][2], vhi[ks & 1][3]);
;         } else {
;             TR_WAIT4(0, vlo[ks & 1][0], vlo[ks & 1][1], vlo[ks & 1][2], vlo[ks & 1][3]); TR_WAIT4(0, vhi[ks & 1][0], vhi[ks & 1][1], vhi[ks & 1][2], vhi[ks & 1][3]);
;         }
;         __builtin_amdgcn_sched_barrier(0);
; #pragma unroll
;         for (int d = 0; d < 4; ++d) { const bf16x8 a = __builtin_shufflevector(vlo[ks & 1][d], vhi[ks & 1][d], 0, 1, 2, 3, 4, 5, 6, 7);
;             o[d] = __builtin_amdgcn_mfma_f32_32x32x16_bf16(a, pb[ks], o[d], 0, 0, 0); }
;         __builtin_amdgcn_sched_barrier(0);
;     }
; }
.LBB0_1016:
	s_cmp_lg_u32 s16, 0
	s_cselect_b64 s[4:5], -1, 0
	s_and_b64 s[4:5], s[0:1], s[4:5]
	s_cmp_le_u32 s16, s51
	s_cselect_b64 s[62:63], -1, 0
	s_and_b64 s[4:5], s[4:5], s[62:63]
	s_andn2_b64 vcc, exec, s[4:5]
	s_cbranch_vccnz .LBB0_1018
	s_mul_i32 s4, s17, 0xb400
	v_add_u32_e32 v80, s77, v222
	v_add_u32_e32 v186, 0x6400, v80
	ds_read_b64_tr_b16 v[80:81], v186 offset:0
	ds_read_b64_tr_b16 v[82:83], v186 offset:2560
	ds_read_b64_tr_b16 v[84:85], v186 offset:64
	ds_read_b64_tr_b16 v[86:87], v186 offset:2624
	ds_read_b64_tr_b16 v[88:89], v186 offset:128
	ds_read_b64_tr_b16 v[90:91], v186 offset:2688
	ds_read_b64_tr_b16 v[92:93], v186 offset:192
	ds_read_b64_tr_b16 v[94:95], v186 offset:2752
	ds_read_b64_tr_b16 v[170:171], v186 offset:5120
	ds_read_b64_tr_b16 v[172:173], v186 offset:7680
	ds_read_b64_tr_b16 v[174:175], v186 offset:5184
	ds_read_b64_tr_b16 v[176:177], v186 offset:7744
	ds_read_b64_tr_b16 v[178:179], v186 offset:5248
	ds_read_b64_tr_b16 v[180:181], v186 offset:7808
	ds_read_b64_tr_b16 v[182:183], v186 offset:5312
	ds_read_b64_tr_b16 v[184:185], v186 offset:7872
	s_nop 0
	s_waitcnt lgkmcnt(8)
	s_waitcnt lgkmcnt(8)
	s_nop 0
	s_setprio 1
	v_mfma_f32_32x32x16_bf16 v[48:63], v[80:83], v[76:79], v[48:63]
	v_mfma_f32_32x32x16_bf16 v[32:47], v[84:87], v[76:79], v[32:47]
	v_mfma_f32_32x32x16_bf16 v[16:31], v[88:91], v[76:79], v[16:31]
	v_mfma_f32_32x32x16_bf16 v[0:15], v[92:95], v[76:79], v[0:15]
	ds_read_b64_tr_b16 v[80:81], v186 offset:10240
	ds_read_b64_tr_b16 v[82:83], v186 offset:12800
	ds_read_b64_tr_b16 v[84:85], v186 offset:10304
	ds_read_b64_tr_b16 v[86:87], v186 offset:12864
	ds_read_b64_tr_b16 v[88:89], v186 offset:10368
	ds_read_b64_tr_b16 v[90:91], v186 offset:12928
	ds_read_b64_tr_b16 v[92:93], v186 offset:10432
	ds_read_b64_tr_b16 v[94:95], v186 offset:12992
	s_waitcnt lgkmcnt(8)
	s_waitcnt lgkmcnt(8)
	s_nop 0
	v_mfma_f32_32x32x16_bf16 v[48:63], v[170:173], v[72:75], v[48:63]
	v_mfma_f32_32x32x16_bf16 v[32:47], v[174:177], v[72:75], v[32:47]
	v_mfma_f32_32x32x16_bf16 v[16:31], v[178:181], v[72:75], v[16:31]
	v_mfma_f32_32x32x16_bf16 v[0:15], v[182:185], v[72:75], v[0:15]
	ds_read_b64_tr_b16 v[170:171], v186 offset:15360
	ds_read_b64_tr_b16 v[172:173], v186 offset:17920
	ds_read_b64_tr_b16 v[174:175], v186 offset:15424
	ds_read_b64_tr_b16 v[176:177], v186 offset:17984
	ds_read_b64_tr_b16 v[178:179], v186 offset:15488
	ds_read_b64_tr_b16 v[180:181], v186 offset:18048
	ds_read_b64_tr_b16 v[182:183], v186 offset:15552
	ds_read_b64_tr_b16 v[184:185], v186 offset:18112
	s_waitcnt lgkmcnt(8)
	s_waitcnt lgkmcnt(8)
	s_nop 0
	v_mfma_f32_32x32x16_bf16 v[48:63], v[80:83], v[68:71], v[48:63]
	v_mfma_f32_32x32x16_bf16 v[32:47], v[84:87], v[68:71], v[32:47]
	v_mfma_f32_32x32x16_bf16 v[16:31], v[88:91], v[68:71], v[16:31]
	v_mfma_f32_32x32x16_bf16 v[0:15], v[92:95], v[68:71], v[0:15]
	s_waitcnt lgkmcnt(0)
	s_waitcnt lgkmcnt(0)
	s_nop 0
	v_mfma_f32_32x32x16_bf16 v[48:63], v[170:173], v[64:67], v[48:63]
	v_mfma_f32_32x32x16_bf16 v[32:47], v[174:177], v[64:67], v[32:47]
	v_mfma_f32_32x32x16_bf16 v[16:31], v[178:181], v[64:67], v[16:31]
	v_mfma_f32_32x32x16_bf16 v[0:15], v[182:185], v[64:67], v[0:15]
	s_setprio 0
.LBB0_1018:
	s_cmp_gt_u32 s16, s6
	s_cselect_b64 s[16:17], -1, 0
	s_and_b64 vcc, exec, s[16:17]
	s_mul_i32 s61, s58, 0xb400
	s_cbranch_vccnz .Latt_skipq
	v_add_u32_e32 v194, s74, v223
	ds_read_b128 v[64:67], v194
	ds_read_b128 v[170:173], v194 offset:32
	ds_read_b128 v[174:177], v194 offset:12832
	ds_read_b128 v[178:181], v194 offset:12864
	ds_read_b128 v[182:185], v194 offset:64
	ds_read_b128 v[68:71], v194 offset:12800
	s_waitcnt lgkmcnt(0)
	s_setprio 1
	v_mfma_f32_32x32x16_bf16 v[80:95], v[64:67], v[96:99], 0
	v_mfma_f32_32x32x16_bf16 v[64:79], v[68:71], v[96:99], 0
	ds_read_b128 v[186:189], v194 offset:96
	ds_read_b128 v[190:193], v194 offset:12896
	v_mfma_f32_32x32x16_bf16 v[80:95], v[170:173], v[100:103], v[80:95]
	v_mfma_f32_32x32x16_bf16 v[64:79], v[174:177], v[100:103], v[64:79]
	ds_read_b128 v[170:173], v194 offset:128
	ds_read_b128 v[174:177], v194 offset:12928
	v_mfma_f32_32x32x16_bf16 v[80:95], v[182:185], v[104:107], v[80:95]
	v_mfma_f32_32x32x16_bf16 v[64:79], v[178:181], v[104:107], v[64:79]
	ds_read_b128 v[178:181], v194 offset:160
	ds_read_b128 v[182:185], v194 offset:12960
	s_waitcnt lgkmcnt(0)
	v_mfma_f32_32x32x16_bf16 v[80:95], v[186:189], v[108:111], v[80:95]
	v_mfma_f32_32x32x16_bf16 v[64:79], v[190:193], v[108:111], v[64:79]
	ds_read_b128 v[186:189], v194 offset:192
	ds_read_b128 v[190:193], v194 offset:12992
	v_mfma_f32_32x32x16_bf16 v[80:95], v[170:173], v[112:115], v[80:95]
	v_mfma_f32_32x32x16_bf16 v[64:79], v[174:177], v[112:115], v[64:79]
	ds_read_b128 v[170:173], v194 offset:224
	ds_read_b128 v[174:177], v194 offset:13024
	v_mfma_f32_32x32x16_bf16 v[80:95], v[178:181], v[116:119], v[80:95]
	v_mfma_f32_32x32x16_bf16 v[64:79], v[182:185], v[116:119], v[64:79]
	ds_read_b128 v[178:181], v194 offset:256
	ds_read_b128 v[182:185], v194 offset:13056
	s_waitcnt lgkmcnt(0)
	v_mfma_f32_32x32x16_bf16 v[80:95], v[186:189], v[120:123], v[80:95]
	v_mfma_f32_32x32x16_bf16 v[64:79], v[190:193], v[120:123], v[64:79]
	ds_read_b128 v[186:189], v194 offset:288
	ds_read_b128 v[190:193], v194 offset:13088
	v_mfma_f32_32x32x16_bf16 v[80:95], v[170:173], v[124:127], v[80:95]
	v_mfma_f32_32x32x16_bf16 v[64:79], v[174:177], v[124:127], v[64:79]
	ds_read_b128 v[170:173], v194 offset:320
	ds_read_b128 v[174:177], v194 offset:13120
	v_mfma_f32_32x32x16_bf16 v[80:95], v[178:181], v[128:131], v[80:95]
	v_mfma_f32_32x32x16_bf16 v[64:79], v[182:185], v[128:131], v[64:79]
	ds_read_b128 v[178:181], v194 offset:352
	ds_read_b128 v[182:185], v194 offset:13152
	s_waitcnt lgkmcnt(0)
	v_mfma_f32_32x32x16_bf16 v[80:95], v[186:189], v[132:135], v[80:95]
	v_mfma_f32_32x32x16_bf16 v[64:79], v[190:193], v[132:135], v[64:79]
	v_mfma_f32_32x32x16_bf16 v[80:95], v[170:173], v[136:139], v[80:95]
	v_mfma_f32_32x32x16_bf16 v[64:79], v[174:177], v[136:139], v[64:79]
	v_mfma_f32_32x32x16_bf16 v[80:95], v[178:181], v[140:143], v[80:95]
	v_mfma_f32_32x32x16_bf16 v[64:79], v[182:185], v[140:143], v[64:79]
	s_setprio 0
	s_cmp_lg_u32 s83, 0
	s_cbranch_scc0 .Latt_noissue_q
	s_mov_b64 s[4:5], s[10:11]
	s_cmp_eq_u32 s33, 0
	s_cselect_b32 s82, s76, s80
	s_add_i32 m0, s76, s19
	v_lshl_add_u64 v[172:173], s[4:5], 0, v[144:145]
	global_load_lds_dwordx4 v[172:173], off
	s_add_i32 m0, s76, s20
	v_lshl_add_u64 v[172:173], s[4:5], 0, v[146:147]
	global_load_lds_dwordx4 v[172:173], off
	s_add_i32 m0, s76, s21
	v_lshl_add_u64 v[172:173], s[4:5], 0, v[148:149]
	global_load_lds_dwordx4 v[172:173], off
	s_add_i32 m0, s82, s22
	v_lshl_add_u64 v[172:173], s[4:5], 0, v[150:151]
	global_load_lds_dwordx4 v[172:173], off
	s_add_i32 m0, s80, s23
	v_lshl_add_u64 v[172:173], s[4:5], 0, v[156:157]
	global_load_lds_dwordx4 v[172:173], off
	s_add_i32 m0, s80, s24
	v_lshl_add_u64 v[172:173], s[4:5], 0, v[154:155]
	global_load_lds_dwordx4 v[172:173], off
	s_branch .Latt_issued_q

; #define LAS __attribute__((address_space(3)))
; #define TR_READ(dst, addr, off) asm volatile("ds_read_b64_tr_b16 %0, %1 offset:%c2" : "=v"(dst) : "v"(addr), "i"(off) : "memory")
; #define TR_WAIT4(n, a, b, c, d) asm volatile("s_waitcnt lgkmcnt(" #n ")" : "+v"(a), "+v"(b), "+v"(c), "+v"(d) :: "memory")
; __device__ __forceinline__ void att_pv(const LAS unsigned char* kb, int vlane, const bf16x8 (&pb)[4], f32x16 (&o)[4]) {
;     constexpr int VP = 320;
;     s16x4 vlo[2][4], vhi[2][4];
;     const unsigned vaddr = (unsigned)(unsigned long)(kb + vlane);
; #pragma unroll
;     for (int d = 0; d < 4; ++d) { TR_READ(vlo[0][d], vaddr, d * 64); TR_READ(vhi[0][d], vaddr, 8 * VP + d * 64); }
; #pragma unroll
;     for (int ks = 0; ks < 4; ++ks) {
;         if (ks < 3) {
; #pragma unroll
;             for (int d = 0; d < 4; ++d) { TR_READ(vlo[(ks + 1) & 1][d], vaddr, ((ks + 1) * 16) * VP + d * 64); TR_READ(vhi[(ks + 1) & 1][d], vaddr, ((ks + 1) * 16 + 8) * VP + d * 64); }
;             TR_WAIT4(8, vlo[ks & 1][0], vlo[ks & 1][1], vlo[ks & 1][2], vlo[ks & 1][3]); TR_WAIT4(8, vhi[ks & 1][0], vhi[ks & 1][1], vhi[ks & 1][2], vhi[ks & 1][3]);
;         } else {
;             TR_WAIT4(0, vlo[ks & 1][0], vlo[ks & 1][1], vlo[ks & 1][2], vlo[ks & 1][3]); TR_WAIT4(0, vhi[ks & 1][0], vhi[ks & 1][1], vhi[ks & 1][2], vhi[ks & 1][3]);
;         }
;         __builtin_amdgcn_sched_barrier(0);
; #pragma unroll
;         for (int d = 0; d < 4; ++d) { const bf16x8 a = __builtin_shufflevector(vlo[ks & 1][d], vhi[ks & 1][d], 0, 1, 2, 3, 4, 5, 6, 7);
;             o[d] = __builtin_amdgcn_mfma_f32_32x32x16_bf16(a, pb[ks], o[d], 0, 0, 0); }
;         __builtin_amdgcn_sched_barrier(0);
;     }
; }
; __device__ __forceinline__ void att_mfma(const Params& P, LAS unsigned char* lds, int wave) {
;     ...
;             if (roleA && kt <= my_last) att_pv(lds + bcur * BUF, vlane, pb, o);
.LBB0_1022:
	s_or_b64 s[4:5], s[0:1], s[16:17]
	s_and_b64 vcc, exec, s[4:5]
	s_cbranch_vccnz .LBB0_1024
	v_add_u32_e32 v80, s78, v222
	v_add_u32_e32 v186, 0x6400, v80
	ds_read_b64_tr_b16 v[80:81], v186 offset:0
	ds_read_b64_tr_b16 v[82:83], v186 offset:2560
	ds_read_b64_tr_b16 v[84:85], v186 offset:64
	ds_read_b64_tr_b16 v[86:87], v186 offset:2624
	ds_read_b64_tr_b16 v[88:89], v186 offset:128
	ds_read_b64_tr_b16 v[90:91], v186 offset:2688
	ds_read_b64_tr_b16 v[92:93], v186 offset:192
	ds_read_b64_tr_b16 v[94:95], v186 offset:2752
	ds_read_b64_tr_b16 v[170:171], v186 offset:5120
	ds_read_b64_tr_b16 v[172:173], v186 offset:7680
	ds_read_b64_tr_b16 v[174:175], v186 offset:5184
	ds_read_b64_tr_b16 v[176:177], v186 offset:7744
	ds_read_b64_tr_b16 v[178:179], v186 offset:5248
	ds_read_b64_tr_b16 v[180:181], v186 offset:7808
	ds_read_b64_tr_b16 v[182:183], v186 offset:5312
	ds_read_b64_tr_b16 v[184:185], v186 offset:7872
	s_nop 0
	s_waitcnt lgkmcnt(8)
	s_waitcnt lgkmcnt(8)
	s_nop 0
	s_setprio 1
	v_mfma_f32_32x32x16_bf16 v[48:63], v[80:83], v[76:79], v[48:63]
	v_mfma_f32_32x32x16_bf16 v[32:47], v[84:87], v[76:79], v[32:47]
	v_mfma_f32_32x32x16_bf16 v[16:31], v[88:91], v[76:79], v[16:31]
	v_mfma_f32_32x32x16_bf16 v[0:15], v[92:95], v[76:79], v[0:15]
	ds_read_b64_tr_b16 v[80:81], v186 offset:10240
	ds_read_b64_tr_b16 v[82:83], v186 offset:12800
	ds_read_b64_tr_b16 v[84:85], v186 offset:10304
	ds_read_b64_tr_b16 v[86:87], v186 offset:12864
	ds_read_b64_tr_b16 v[88:89], v186 offset:10368
	ds_read_b64_tr_b16 v[90:91], v186 offset:12928
	ds_read_b64_tr_b16 v[92:93], v186 offset:10432
	ds_read_b64_tr_b16 v[94:95], v186 offset:12992
	s_waitcnt lgkmcnt(8)
	s_waitcnt lgkmcnt(8)
	s_nop 0
	v_mfma_f32_32x32x16_bf16 v[48:63], v[170:173], v[72:75], v[48:63]
	v_mfma_f32_32x32x16_bf16 v[32:47], v[174:177], v[72:75], v[32:47]
	v_mfma_f32_32x32x16_bf16 v[16:31], v[178:181], v[72:75], v[16:31]
	v_mfma_f32_32x32x16_bf16 v[0:15], v[182:185], v[72:75], v[0:15]
	ds_read_b64_tr_b16 v[170:171], v186 offset:15360
	ds_read_b64_tr_b16 v[172:173], v186 offset:17920
	ds_read_b64_tr_b16 v[174:175], v186 offset:15424
	ds_read_b64_tr_b16 v[176:177], v186 offset:17984
	ds_read_b64_tr_b16 v[178:179], v186 offset:15488
	ds_read_b64_tr_b16 v[180:181], v186 offset:18048
	ds_read_b64_tr_b16 v[182:183], v186 offset:15552
	ds_read_b64_tr_b16 v[184:185], v186 offset:18112
	s_waitcnt lgkmcnt(8)
	s_waitcnt lgkmcnt(8)
	s_nop 0
	v_mfma_f32_32x32x16_bf16 v[48:63], v[80:83], v[68:71], v[48:63]
	v_mfma_f32_32x32x16_bf16 v[32:47], v[84:87], v[68:71], v[32:47]
	v_mfma_f32_32x32x16_bf16 v[16:31], v[88:91], v[68:71], v[16:31]
	v_mfma_f32_32x32x16_bf16 v[0:15], v[92:95], v[68:71], v[0:15]
	s_waitcnt lgkmcnt(0)
	s_waitcnt lgkmcnt(0)
	s_nop 0
	v_mfma_f32_32x32x16_bf16 v[48:63], v[170:173], v[64:67], v[48:63]
	v_mfma_f32_32x32x16_bf16 v[32:47], v[174:177], v[64:67], v[32:47]
	v_mfma_f32_32x32x16_bf16 v[16:31], v[178:181], v[64:67], v[16:31]
	v_mfma_f32_32x32x16_bf16 v[0:15], v[182:185], v[64:67], v[0:15]
	s_setprio 0
